# GDN scan as well: packed fp32 FMAs near MFMAs split into two v_fma_f32 (on top of the mLSTM split)
# baseline (speedup 1.0000x reference)
; #define LAS __attribute__((address_space(3)))
; __device__ __forceinline__ f32x4 unpack4(const v2u w) { f32x4 r; r[0] = bflo(w.x); r[1] = bfhi(w.x); r[2] = bflo(w.y); r[3] = bfhi(w.y); return r; }
; template <class T> __device__ __forceinline__ T ldun(const void* ubase, unsigned boff) { return __builtin_nontemporal_load((const GAS T*)((const GAS char*)ubase + boff)); }
; __device__ __forceinline__ const char* upin(const char* p) { asm volatile("" : "+s"(p)); return p; }
; __device__ __forceinline__ char* upin(char* p) { asm volatile("" : "+s"(p)); return p; }
; template <bool GDN, int NT> __device__ __forceinline__ void scan_load(const Frame& F, int b, int h, int dir, const ScanLane& L, int s, ScanOps<NT>& o) {
;     ...
;         const char* base = (const char*)F.PG + (size_t)ud * 32768;
;         const char* bM = upin(base); const char* bB = upin(base + 8192); const char* bQ = upin(base + 16384); const char* bO = upin(base + 24576);
; #pragma unroll
;         for (int ks = 0; ks < 2; ++ks) { o.Mf[ks] = ldun<bf16x8>(bM + ks * 1024, L.o16); o.Qf[ks] = ldun<bf16x8>(bQ + ks * 1024, L.o16); }
; #pragma unroll
;         for (int pr = 0; pr < 2; ++pr) { const v4u qb = ldun<v4u>(bB + pr * 1024, L.o16p), qo = ldun<v4u>(bO + pr * 1024, L.o16p);
;             o.bv[2 * pr] = (v2u){qb.x, qb.y}; o.bv[2 * pr + 1] = (v2u){qb.z, qb.w}; o.ov[2 * pr] = (v2u){qo.x, qo.y}; o.ov[2 * pr + 1] = (v2u){qo.z, qo.w}; }
;         o.wi = (f32x4){1.f, 1.f, 1.f, 1.f};
;     ...
;     const float gl = ((const LAS float*)(St + 4 * 80 * 72))[(dir ? (s < 4 ? 3 - s : 39 - s) : s) * 2 + dir];
;     f32x4 O[NT];
; #pragma unroll
;     for (int t = 0; t < NT; ++t) {
;         const LAS bf16_t* sp2 = Sb + (16 * t + lr) * 72 + 8 * lq;
;         const bf16x8 s0 = *(const LAS bf16x8*)sp2, s1 = *(const LAS bf16x8*)(sp2 + 32);
;         const f32x4 bv = unpack4(use.bv[t]), ov = unpack4(use.ov[t]);
;         if (GDN) {
;             f32x4 o = ov, sn = S[t] * gl + bv;
;             o = __builtin_amdgcn_mfma_f32_16x16x32_bf16(use.Qf[0], s0, o, 0, 0, 0); o = __builtin_amdgcn_mfma_f32_16x16x32_bf16(use.Qf[1], s1, o, 0, 0, 0);
;             sn = __builtin_amdgcn_mfma_f32_16x16x32_bf16(use.Mf[0], s0, sn, 0, 0, 0); sn = __builtin_amdgcn_mfma_f32_16x16x32_bf16(use.Mf[1], s1, sn, 0, 0, 0);
;             S[t] = sn; O[t] = o;
.LBB0_481:
	s_add_i32 s0, s23, 5
	s_min_u32 s3, s0, 33
	s_add_i32 s6, s3, 2
	s_sub_i32 s3, 37, s3
	s_and_b64 s[4:5], s[90:91], exec
	s_cselect_b32 s3, s6, s3
	s_add_i32 s3, s3, s30
	s_lshl_b32 s3, s3, 1
	s_add_i32 s4, s3, s68
	s_ashr_i32 s5, s4, 31
	s_lshl_b64 s[4:5], s[4:5], 15
	s_add_u32 s4, s35, s4
	s_addc_u32 s5, s43, s5
	s_add_u32 s8, s4, 0x2000
	s_addc_u32 s9, s5, 0
	s_add_u32 s10, s4, 0x4000
	s_addc_u32 s11, s5, 0
	s_mov_b64 s[6:7], s[4:5]
	s_add_u32 s4, s4, 0x6000
	s_addc_u32 s5, s5, 0
	global_load_dwordx4 v[70:73], v18, s[8:9] nt
	global_load_dwordx4 v[66:69], v18, s[4:5] nt
	global_load_dwordx4 v[22:25], v18, s[8:9] offset:1024 nt
	s_nop 0
	global_load_dwordx4 v[18:21], v18, s[4:5] offset:1024 nt
	s_add_i32 s3, s22, 37
	s_and_b64 s[4:5], s[90:91], exec
	s_cselect_b32 s0, s0, s3
	s_lshl_b32 s0, s0, 3
	s_add_i32 s0, s34, s0
	v_lshl_add_u64 v[146:147], s[6:7], 0, v[0:1]
	v_lshl_add_u64 v[148:149], s[10:11], 0, v[0:1]
	v_mov_b32_e32 v0, s0
	ds_read_b32 v0, v0 offset:46080
	ds_read_b128 v[98:101], v200 offset:11520
	ds_read_b128 v[102:105], v200 offset:11584
	ds_read_b128 v[212:215], v200 offset:13824
	ds_read_b128 v[216:219], v200 offset:13888
	ds_read_b128 v[224:227], v200 offset:16128
	ds_read_b128 v[242:245], v200 offset:16192
	v_lshlrev_b32_e32 v110, 16, v94
	v_and_b32_e32 v111, 0xffff0000, v94
	v_lshlrev_b32_e32 v112, 16, v95
	v_and_b32_e32 v113, 0xffff0000, v95
	v_lshlrev_b32_e32 v106, 16, v86
	v_and_b32_e32 v107, 0xffff0000, v86
	v_lshlrev_b32_e32 v108, 16, v87
	v_and_b32_e32 v109, 0xffff0000, v87
	s_waitcnt lgkmcnt(6)
	v_fma_f32 v112, v128, v0, v112
	v_fma_f32 v113, v129, v0, v113
	v_fma_f32 v110, v126, v0, v110
	v_fma_f32 v111, v127, v0, v111
	s_waitcnt lgkmcnt(5)
	v_mfma_f32_16x16x32_bf16 v[106:109], v[46:49], v[98:101], v[106:109]
	s_mov_b64 s[6:7], 0x400
	v_lshl_add_u64 v[150:151], v[146:147], 0, s[6:7]
	v_lshl_add_u64 v[152:153], v[148:149], 0, s[6:7]
	v_mfma_f32_16x16x32_bf16 v[98:101], v[30:33], v[98:101], v[110:113]
	s_add_i32 s3, s22, -6
	s_mov_b64 s[20:21], 0
	s_waitcnt lgkmcnt(4)
	v_mfma_f32_16x16x32_bf16 v[130:133], v[34:37], v[102:105], v[106:109]
	v_lshlrev_b32_e32 v110, 16, v96
	v_and_b32_e32 v111, 0xffff0000, v96
	v_lshlrev_b32_e32 v112, 16, v97
	v_mfma_f32_16x16x32_bf16 v[126:129], v[26:29], v[102:105], v[98:101]
	s_nop 2
	v_and_b32_e32 v113, 0xffff0000, v97
	v_lshlrev_b32_e32 v106, 16, v88
	v_and_b32_e32 v107, 0xffff0000, v88
	v_lshlrev_b32_e32 v108, 16, v89
	v_and_b32_e32 v109, 0xffff0000, v89
	v_fma_f32 v112, v124, v0, v112
	v_fma_f32 v113, v125, v0, v113
	v_fma_f32 v110, v122, v0, v110
	v_fma_f32 v111, v123, v0, v111
	s_waitcnt lgkmcnt(3)
	v_mfma_f32_16x16x32_bf16 v[106:109], v[46:49], v[212:215], v[106:109]
	v_mfma_f32_16x16x32_bf16 v[98:101], v[30:33], v[212:215], v[110:113]
	s_waitcnt lgkmcnt(2)
	v_mfma_f32_16x16x32_bf16 v[134:137], v[34:37], v[216:219], v[106:109]
	v_lshlrev_b32_e32 v110, 16, v78
	v_and_b32_e32 v111, 0xffff0000, v78
	v_lshlrev_b32_e32 v112, 16, v79
	v_mfma_f32_16x16x32_bf16 v[122:125], v[26:29], v[216:219], v[98:101]
	ds_read_b128 v[212:215], v200 offset:18432
	ds_read_b128 v[216:219], v200 offset:18496
	s_nop 2
	v_and_b32_e32 v113, 0xffff0000, v79
	v_lshlrev_b32_e32 v106, 16, v74
	v_and_b32_e32 v107, 0xffff0000, v74
	v_lshlrev_b32_e32 v108, 16, v75
	v_and_b32_e32 v109, 0xffff0000, v75
	v_fma_f32 v112, v116, v0, v112
	v_fma_f32 v113, v117, v0, v113
	v_fma_f32 v110, v114, v0, v110
	v_fma_f32 v111, v115, v0, v111
	s_waitcnt lgkmcnt(3)
	v_mfma_f32_16x16x32_bf16 v[106:109], v[46:49], v[224:227], v[106:109]
	v_mfma_f32_16x16x32_bf16 v[98:101], v[30:33], v[224:227], v[110:113]
	s_waitcnt lgkmcnt(2)
	v_mfma_f32_16x16x32_bf16 v[138:141], v[34:37], v[242:245], v[106:109]
	s_nop 0
	v_lshlrev_b32_e32 v110, 16, v80
	v_and_b32_e32 v111, 0xffff0000, v80
	v_lshlrev_b32_e32 v112, 16, v81
	v_mfma_f32_16x16x32_bf16 v[114:117], v[26:29], v[242:245], v[98:101]
	s_nop 2
	v_and_b32_e32 v113, 0xffff0000, v81
	v_lshlrev_b32_e32 v106, 16, v76
	v_and_b32_e32 v107, 0xffff0000, v76
	v_lshlrev_b32_e32 v108, 16, v77
	v_and_b32_e32 v109, 0xffff0000, v77
	v_fma_f32 v112, v120, v0, v112
	v_fma_f32 v113, v121, v0, v113
	v_fma_f32 v110, v118, v0, v110
	v_fma_f32 v111, v119, v0, v111
	s_waitcnt lgkmcnt(1)
	v_mfma_f32_16x16x32_bf16 v[106:109], v[46:49], v[212:215], v[106:109]
	v_mfma_f32_16x16x32_bf16 v[98:101], v[30:33], v[212:215], v[110:113]
	s_waitcnt lgkmcnt(0)
	v_mfma_f32_16x16x32_bf16 v[142:145], v[34:37], v[216:219], v[106:109]
	v_mfma_f32_16x16x32_bf16 v[118:121], v[26:29], v[216:219], v[98:101]

; #define LAS __attribute__((address_space(3)))
; __device__ __forceinline__ f32x4 unpack4(const v2u w) { f32x4 r; r[0] = bflo(w.x); r[1] = bfhi(w.x); r[2] = bflo(w.y); r[3] = bfhi(w.y); return r; }
; template <class T> __device__ __forceinline__ T ldun(const void* ubase, unsigned boff) { return __builtin_nontemporal_load((const GAS T*)((const GAS char*)ubase + boff)); }
; __device__ __forceinline__ const char* upin(const char* p) { asm volatile("" : "+s"(p)); return p; }
; __device__ __forceinline__ char* upin(char* p) { asm volatile("" : "+s"(p)); return p; }
; template <bool GDN, int NT> __device__ __forceinline__ void scan_load(const Frame& F, int b, int h, int dir, const ScanLane& L, int s, ScanOps<NT>& o) {
;     ...
;         const char* base = (const char*)F.PG + (size_t)ud * 32768;
;         const char* bM = upin(base); const char* bB = upin(base + 8192); const char* bQ = upin(base + 16384); const char* bO = upin(base + 24576);
; #pragma unroll
;         for (int ks = 0; ks < 2; ++ks) { o.Mf[ks] = ldun<bf16x8>(bM + ks * 1024, L.o16); o.Qf[ks] = ldun<bf16x8>(bQ + ks * 1024, L.o16); }
; #pragma unroll
;         for (int pr = 0; pr < 2; ++pr) { const v4u qb = ldun<v4u>(bB + pr * 1024, L.o16p), qo = ldun<v4u>(bO + pr * 1024, L.o16p);
;             o.bv[2 * pr] = (v2u){qb.x, qb.y}; o.bv[2 * pr + 1] = (v2u){qb.z, qb.w}; o.ov[2 * pr] = (v2u){qo.x, qo.y}; o.ov[2 * pr + 1] = (v2u){qo.z, qo.w}; }
;         o.wi = (f32x4){1.f, 1.f, 1.f, 1.f};
;     ...
;     const float gl = ((const LAS float*)(St + 4 * 80 * 72))[(dir ? (s < 4 ? 3 - s : 39 - s) : s) * 2 + dir];
;     f32x4 O[NT];
; #pragma unroll
;     for (int t = 0; t < NT; ++t) {
;         const LAS bf16_t* sp2 = Sb + (16 * t + lr) * 72 + 8 * lq;
;         const bf16x8 s0 = *(const LAS bf16x8*)sp2, s1 = *(const LAS bf16x8*)(sp2 + 32);
;         const f32x4 bv = unpack4(use.bv[t]), ov = unpack4(use.ov[t]);
;         if (GDN) {
;             f32x4 o = ov, sn = S[t] * gl + bv;
;             o = __builtin_amdgcn_mfma_f32_16x16x32_bf16(use.Qf[0], s0, o, 0, 0, 0); o = __builtin_amdgcn_mfma_f32_16x16x32_bf16(use.Qf[1], s1, o, 0, 0, 0);
;             sn = __builtin_amdgcn_mfma_f32_16x16x32_bf16(use.Mf[0], s0, sn, 0, 0, 0); sn = __builtin_amdgcn_mfma_f32_16x16x32_bf16(use.Mf[1], s1, sn, 0, 0, 0);
;             S[t] = sn; O[t] = o;
.LBB0_496:
	s_min_u32 s1, s23, 33
	s_add_i32 s1, s1, 2
	s_and_b64 s[4:5], exec, s[10:11]
	s_cselect_b32 s3, 3, 39
	s_sub_i32 s3, s3, s1
	s_and_b64 s[4:5], s[90:91], exec
	s_cselect_b32 s1, s1, s3
	s_add_i32 s1, s1, s30
	s_lshl_b32 s1, s1, 1
	s_add_i32 s4, s1, s68
	s_ashr_i32 s5, s4, 31
	s_lshl_b64 s[4:5], s[4:5], 15
	s_add_u32 s4, s35, s4
	s_addc_u32 s5, s43, s5
	s_add_u32 s8, s4, 0x2000
	s_addc_u32 s9, s5, 0
	s_add_u32 s12, s4, 0x4000
	s_addc_u32 s13, s5, 0
	s_mov_b64 s[6:7], s[4:5]
	s_add_u32 s4, s4, 0x6000
	s_addc_u32 s5, s5, 0
	global_load_dwordx4 v[30:33], v146, s[6:7] nt
	global_load_dwordx4 v[46:49], v146, s[12:13] nt
	global_load_dwordx4 v[26:29], v146, s[6:7] offset:1024 nt
	global_load_dwordx4 v[34:37], v146, s[12:13] offset:1024 nt
	global_load_dwordx4 v[94:97], v0, s[8:9] nt
	global_load_dwordx4 v[86:89], v0, s[4:5] nt
	global_load_dwordx4 v[78:81], v0, s[8:9] offset:1024 nt
	global_load_dwordx4 v[74:77], v0, s[4:5] offset:1024 nt
	s_cmp_gt_u32 s23, 3
	s_cselect_b32 s1, 39, 3
	s_add_i32 s1, s1, s22
	s_add_i32 s1, s1, 3
	s_and_b64 s[4:5], s[90:91], exec
	s_cselect_b32 s1, s23, s1
	s_lshl_b32 s1, s1, 3
	s_add_i32 s1, s34, s1
	v_mov_b32_e32 v0, s1
	ds_read_b32 v0, v0 offset:46080
	v_add_u32_e32 v146, v198, v155
	ds_read_b128 v[134:137], v146
	ds_read_b128 v[138:141], v146 offset:64
	ds_read_b128 v[212:215], v146 offset:2304
	ds_read_b128 v[216:219], v146 offset:2368
	ds_read_b128 v[224:227], v146 offset:4608
	ds_read_b128 v[242:245], v146 offset:4672
	v_lshlrev_b32_e32 v142, 16, v90
	v_and_b32_e32 v143, 0xffff0000, v90
	v_lshlrev_b32_e32 v90, 16, v91
	v_and_b32_e32 v91, 0xffff0000, v91
	v_lshlrev_b32_e32 v130, 16, v82
	v_and_b32_e32 v131, 0xffff0000, v82
	v_lshlrev_b32_e32 v132, 16, v83
	v_and_b32_e32 v133, 0xffff0000, v83
	s_waitcnt lgkmcnt(6)
	v_fma_f32 v128, v128, v0, v90
	v_fma_f32 v129, v129, v0, v91
	v_fma_f32 v126, v126, v0, v142
	v_fma_f32 v127, v127, v0, v143
	s_waitcnt lgkmcnt(5)
	v_mfma_f32_16x16x32_bf16 v[130:133], v[58:61], v[134:137], v[130:133]
	v_lshlrev_b32_e32 v82, 16, v84
	v_and_b32_e32 v83, 0xffff0000, v84
	v_lshlrev_b32_e32 v84, 16, v85
	v_mfma_f32_16x16x32_bf16 v[126:129], v[42:45], v[134:137], v[126:129]
	v_and_b32_e32 v85, 0xffff0000, v85
	v_lshlrev_b32_e32 v90, 16, v92
	v_and_b32_e32 v91, 0xffff0000, v92
	s_waitcnt lgkmcnt(4)
	v_mfma_f32_16x16x32_bf16 v[130:133], v[50:53], v[138:141], v[130:133]
	v_lshlrev_b32_e32 v92, 16, v93
	v_and_b32_e32 v93, 0xffff0000, v93
	v_fma_f32 v92, v124, v0, v92
	v_fma_f32 v93, v125, v0, v93
	v_mfma_f32_16x16x32_bf16 v[126:129], v[38:41], v[138:141], v[126:129]
	v_fma_f32 v90, v122, v0, v90
	v_fma_f32 v91, v123, v0, v91
	s_waitcnt lgkmcnt(3)
	v_mfma_f32_16x16x32_bf16 v[82:85], v[58:61], v[212:215], v[82:85]
	s_waitcnt lgkmcnt(2)
	v_mfma_f32_16x16x32_bf16 v[134:137], v[50:53], v[216:219], v[82:85]
	v_mfma_f32_16x16x32_bf16 v[82:85], v[42:45], v[212:215], v[90:93]
	v_lshlrev_b32_e32 v138, 16, v54
	v_and_b32_e32 v139, 0xffff0000, v54
	v_lshlrev_b32_e32 v140, 16, v55
	v_mfma_f32_16x16x32_bf16 v[122:125], v[38:41], v[216:219], v[82:85]
	ds_read_b128 v[212:215], v146 offset:6912
	ds_read_b128 v[216:219], v146 offset:6976
	s_nop 2
	v_lshlrev_b32_e32 v142, 16, v62
	v_and_b32_e32 v143, 0xffff0000, v62
	v_lshlrev_b32_e32 v62, 16, v63
	v_and_b32_e32 v63, 0xffff0000, v63
	v_and_b32_e32 v141, 0xffff0000, v55
	v_fma_f32 v116, v116, v0, v62
	v_fma_f32 v117, v117, v0, v63
	v_fma_f32 v114, v114, v0, v142
	v_fma_f32 v115, v115, v0, v143
	s_waitcnt lgkmcnt(3)
	v_mfma_f32_16x16x32_bf16 v[138:141], v[58:61], v[224:227], v[138:141]
	v_lshlrev_b32_e32 v62, 16, v64
	v_and_b32_e32 v63, 0xffff0000, v64
	v_lshlrev_b32_e32 v64, 16, v65
	v_mfma_f32_16x16x32_bf16 v[82:85], v[42:45], v[224:227], v[114:117]
	v_and_b32_e32 v65, 0xffff0000, v65
	v_lshlrev_b32_e32 v54, 16, v56
	v_and_b32_e32 v55, 0xffff0000, v56
	s_waitcnt lgkmcnt(2)
	v_mfma_f32_16x16x32_bf16 v[138:141], v[50:53], v[242:245], v[138:141]
	v_lshlrev_b32_e32 v56, 16, v57
	v_and_b32_e32 v57, 0xffff0000, v57
	v_fma_f32 v64, v120, v0, v64
	v_fma_f32 v65, v121, v0, v65
	v_mfma_f32_16x16x32_bf16 v[114:117], v[38:41], v[242:245], v[82:85]
	s_nop 2
	v_fma_f32 v62, v118, v0, v62
	v_fma_f32 v63, v119, v0, v63
	s_waitcnt lgkmcnt(1)
	v_mfma_f32_16x16x32_bf16 v[54:57], v[58:61], v[212:215], v[54:57]
	v_mfma_f32_16x16x32_bf16 v[42:45], v[42:45], v[212:215], v[62:65]
	s_waitcnt lgkmcnt(0)
	v_mfma_f32_16x16x32_bf16 v[142:145], v[50:53], v[216:219], v[54:57]
	v_mfma_f32_16x16x32_bf16 v[118:121], v[38:41], v[216:219], v[42:45]

; template <bool GDN, int NT> __device__ __forceinline__ void scan_load(const Frame& F, int b, int h, int dir, const ScanLane& L, int s, ScanOps<NT>& o) {
;     ...
;         const char* base = (const char*)F.PG + (size_t)ud * 32768;
;         const char* bM = upin(base); const char* bB = upin(base + 8192); const char* bQ = upin(base + 16384); const char* bO = upin(base + 24576);
; #pragma unroll
;         for (int ks = 0; ks < 2; ++ks) { o.Mf[ks] = ldun<bf16x8>(bM + ks * 1024, L.o16); o.Qf[ks] = ldun<bf16x8>(bQ + ks * 1024, L.o16); }
; #pragma unroll
;         for (int pr = 0; pr < 2; ++pr) { const v4u qb = ldun<v4u>(bB + pr * 1024, L.o16p), qo = ldun<v4u>(bO + pr * 1024, L.o16p);
;             o.bv[2 * pr] = (v2u){qb.x, qb.y}; o.bv[2 * pr + 1] = (v2u){qb.z, qb.w}; o.ov[2 * pr] = (v2u){qo.x, qo.y}; o.ov[2 * pr + 1] = (v2u){qo.z, qo.w}; }
;         o.wi = (f32x4){1.f, 1.f, 1.f, 1.f};
;     ...
;     if (s < 36) {
; #pragma unroll
;         for (int t = 0; t < NT; ++t) *(LAS v2u*)(Sb + (16 * t + lr) * 72 + 16 * wq + 4 * lq) = pack4(S[t]); }
;     if (s == 21 || s == 3) asm volatile("s_waitcnt vmcnt(0)" ::: "memory");
;     else if (scan_needfin(s - 1)) { if (GDN) asm volatile("s_waitcnt vmcnt(14)" ::: "memory"); else asm volatile("s_waitcnt vmcnt(15)" ::: "memory"); }
;     else { if (GDN) asm volatile("s_waitcnt vmcnt(8)" ::: "memory"); else asm volatile("s_waitcnt vmcnt(9)" ::: "memory"); }
;     __syncthreads();
;     if (s > 0) {
;         const int sp = s - 1;
;         if (sp == 20 || sp == 2) { asm volatile("s_waitcnt vmcnt(0)" ::: "memory"); scan_fin_load<GDN>(F, b, h, dir, L, sp, PEND, fin); }
;         if (!nofin) scan_finish<GDN>(F, b, h, dir, L, sp, PEND, Oprev, fin);
;     }
;     if (s == 36) return false;
;     if (scan_needfin(s) && ko != 1 && ko != 3) scan_fin_load<GDN>(F, b, h, dir, L, s + 1, PEND, fin);
;     if (ko != 1 && ko != 2) scan_load<GDN, NT>(F, b, h, dir, L, s < 34 ? s + 2 : 35, ld);
;     const float gl = ((const LAS float*)(St + 4 * 80 * 72))[(dir ? (s < 4 ? 3 - s : 39 - s) : s) * 2 + dir];
;     f32x4 O[NT];
; #pragma unroll
;     for (int t = 0; t < NT; ++t) {
;         const LAS bf16_t* sp2 = Sb + (16 * t + lr) * 72 + 8 * lq;
;         const bf16x8 s0 = *(const LAS bf16x8*)sp2, s1 = *(const LAS bf16x8*)(sp2 + 32);
;         const f32x4 bv = unpack4(use.bv[t]), ov = unpack4(use.ov[t]);
;         if (GDN) {
.LBB0_531:
	s_min_u32 s1, s4, 33
	s_add_i32 s8, s1, 2
	s_and_b64 s[6:7], exec, s[10:11]
	s_cselect_b32 s1, 3, 39
	s_sub_i32 s9, s1, s8
	s_and_b64 s[6:7], s[90:91], exec
	s_cselect_b32 s6, s8, s9
	s_add_i32 s6, s6, s30
	s_lshl_b32 s6, s6, 1
	s_add_i32 s6, s6, s68
	s_ashr_i32 s7, s6, 31
	s_lshl_b64 s[6:7], s[6:7], 15
	s_add_u32 s6, s35, s6
	s_addc_u32 s7, s43, s7
	s_add_u32 s10, s6, 0x2000
	s_addc_u32 s11, s7, 0
	s_add_u32 s12, s6, 0x4000
	s_addc_u32 s13, s7, 0
	s_mov_b64 s[8:9], s[6:7]
	s_add_u32 s6, s6, 0x6000
	s_addc_u32 s7, s7, 0
	global_load_dwordx4 v[42:45], v50, s[8:9] nt
	global_load_dwordx4 v[58:61], v50, s[12:13] nt
	global_load_dwordx4 v[38:41], v50, s[8:9] offset:1024 nt
	s_nop 0
	global_load_dwordx4 v[50:53], v50, s[12:13] offset:1024 nt
	s_nop 0
	global_load_dwordx4 v[90:93], v0, s[10:11] nt
	global_load_dwordx4 v[82:85], v0, s[6:7] nt
	global_load_dwordx4 v[62:65], v0, s[10:11] offset:1024 nt
	global_load_dwordx4 v[54:57], v0, s[6:7] offset:1024 nt
	s_add_i32 s5, s5, 2
	s_and_b64 s[6:7], s[90:91], exec
	s_cselect_b32 s5, s4, s5
	s_lshl_b32 s6, s5, 3
	s_add_i32 s6, s34, s6
	v_mov_b32_e32 v0, s6
	ds_read_b32 v0, v0 offset:46080
	v_add_u32_e32 v200, v198, v155
	ds_read_b128 v[134:137], v200 offset:11520
	ds_read_b128 v[138:141], v200 offset:11584
	ds_read_b128 v[212:215], v200 offset:13824
	ds_read_b128 v[216:219], v200 offset:13888
	ds_read_b128 v[224:227], v200 offset:16128
	ds_read_b128 v[242:245], v200 offset:16192
	v_lshlrev_b32_e32 v142, 16, v70
	v_and_b32_e32 v143, 0xffff0000, v70
	v_lshlrev_b32_e32 v144, 16, v71
	v_and_b32_e32 v145, 0xffff0000, v71
	v_lshlrev_b32_e32 v130, 16, v66
	v_and_b32_e32 v131, 0xffff0000, v66
	v_lshlrev_b32_e32 v132, 16, v67
	v_and_b32_e32 v133, 0xffff0000, v67
	s_waitcnt lgkmcnt(6)
	v_fma_f32 v128, v128, v0, v144
	v_fma_f32 v129, v129, v0, v145
	v_fma_f32 v126, v126, v0, v142
	v_fma_f32 v127, v127, v0, v143
	s_waitcnt lgkmcnt(5)
	v_mfma_f32_16x16x32_bf16 v[130:133], v[110:113], v[134:137], v[130:133]
	v_lshlrev_b32_e32 v146, 16, v72
	v_and_b32_e32 v147, 0xffff0000, v72
	v_lshlrev_b32_e32 v148, 16, v73
	v_mfma_f32_16x16x32_bf16 v[126:129], v[102:105], v[134:137], v[126:129]
	v_and_b32_e32 v149, 0xffff0000, v73
	v_lshlrev_b32_e32 v134, 16, v68
	v_and_b32_e32 v135, 0xffff0000, v68
	s_waitcnt lgkmcnt(4)
	v_mfma_f32_16x16x32_bf16 v[130:133], v[106:109], v[138:141], v[130:133]
	v_lshlrev_b32_e32 v136, 16, v69
	v_and_b32_e32 v137, 0xffff0000, v69
	v_fma_f32 v124, v124, v0, v148
	v_fma_f32 v125, v125, v0, v149
	v_mfma_f32_16x16x32_bf16 v[126:129], v[98:101], v[138:141], v[126:129]
	v_fma_f32 v122, v122, v0, v146
	v_fma_f32 v123, v123, v0, v147
	v_lshlrev_b32_e32 v150, 16, v22
	s_waitcnt lgkmcnt(3)
	v_mfma_f32_16x16x32_bf16 v[134:137], v[110:113], v[212:215], v[134:137]
	v_and_b32_e32 v151, 0xffff0000, v22
	v_lshlrev_b32_e32 v152, 16, v23
	v_and_b32_e32 v153, 0xffff0000, v23
	v_mfma_f32_16x16x32_bf16 v[122:125], v[102:105], v[212:215], v[122:125]
	v_lshlrev_b32_e32 v138, 16, v18
	v_and_b32_e32 v139, 0xffff0000, v18
	v_lshlrev_b32_e32 v140, 16, v19
	s_waitcnt lgkmcnt(2)
	v_mfma_f32_16x16x32_bf16 v[134:137], v[106:109], v[216:219], v[134:137]
	v_and_b32_e32 v141, 0xffff0000, v19
	v_fma_f32 v116, v116, v0, v152
	v_fma_f32 v117, v117, v0, v153
	v_fma_f32 v114, v114, v0, v150
	v_fma_f32 v115, v115, v0, v151
	v_mfma_f32_16x16x32_bf16 v[122:125], v[98:101], v[216:219], v[122:125]
	ds_read_b128 v[212:215], v200 offset:18432
	ds_read_b128 v[216:219], v200 offset:18496
	v_lshlrev_b32_e32 v166, 16, v24
	v_and_b32_e32 v167, 0xffff0000, v24
	s_waitcnt lgkmcnt(3)
	v_mfma_f32_16x16x32_bf16 v[138:141], v[110:113], v[224:227], v[138:141]
	v_lshlrev_b32_e32 v168, 16, v25
	v_and_b32_e32 v169, 0xffff0000, v25
	v_fma_f32 v120, v120, v0, v168
	v_fma_f32 v121, v121, v0, v169
	v_mfma_f32_16x16x32_bf16 v[114:117], v[102:105], v[224:227], v[114:117]
	v_lshlrev_b32_e32 v142, 16, v20
	v_and_b32_e32 v143, 0xffff0000, v20
	v_lshlrev_b32_e32 v144, 16, v21
	s_waitcnt lgkmcnt(2)
	v_mfma_f32_16x16x32_bf16 v[138:141], v[106:109], v[242:245], v[138:141]
	v_and_b32_e32 v145, 0xffff0000, v21
	v_fma_f32 v118, v118, v0, v166
	v_fma_f32 v119, v119, v0, v167
	v_mov_b32_e32 v201, v154
	v_mfma_f32_16x16x32_bf16 v[114:117], v[98:101], v[242:245], v[114:117]
	v_mov_b32_e32 v0, v192
	v_mov_b32_e32 v202, v194
	s_waitcnt lgkmcnt(1)
	v_mfma_f32_16x16x32_bf16 v[142:145], v[110:113], v[212:215], v[142:145]
	s_cmp_gt_u32 s23, 33
	v_mfma_f32_16x16x32_bf16 v[118:121], v[102:105], v[212:215], v[118:121]
	v_mov_b32_e32 v147, v193
	v_mov_b32_e32 v148, v195
	v_mov_b32_e32 v146, v197
	s_waitcnt lgkmcnt(0)
	v_mfma_f32_16x16x32_bf16 v[142:145], v[106:109], v[216:219], v[142:145]
	v_mov_b32_e32 v149, v196
	v_mfma_f32_16x16x32_bf16 v[118:121], v[98:101], v[216:219], v[118:121]
	v_mov_b32_e32 v152, v192
	s_cbranch_scc1 .LBB0_533
	v_cvt_pk_bf16_f32 v148, v126, v127
	v_cvt_pk_bf16_f32 v149, v128, v129
	ds_write_b64 v199, v[148:149]
	v_cvt_pk_bf16_f32 v148, v122, v123
	v_cvt_pk_bf16_f32 v149, v124, v125
	ds_write_b64 v199, v[148:149] offset:2304
	v_cvt_pk_bf16_f32 v148, v114, v115
	v_cvt_pk_bf16_f32 v149, v116, v117
	ds_write_b64 v199, v[148:149] offset:4608
	v_cvt_pk_bf16_f32 v148, v118, v119
	v_cvt_pk_bf16_f32 v149, v120, v121
	ds_write_b64 v199, v[148:149] offset:6912

; #define LAS __attribute__((address_space(3)))
; __device__ __forceinline__ f32x4 unpack4(const v2u w) { f32x4 r; r[0] = bflo(w.x); r[1] = bfhi(w.x); r[2] = bflo(w.y); r[3] = bfhi(w.y); return r; }
; template <class T> __device__ __forceinline__ T ldun(const void* ubase, unsigned boff) { return __builtin_nontemporal_load((const GAS T*)((const GAS char*)ubase + boff)); }
; __device__ __forceinline__ const char* upin(const char* p) { asm volatile("" : "+s"(p)); return p; }
; __device__ __forceinline__ char* upin(char* p) { asm volatile("" : "+s"(p)); return p; }
; template <bool GDN, int NT> __device__ __forceinline__ void scan_load(const Frame& F, int b, int h, int dir, const ScanLane& L, int s, ScanOps<NT>& o) {
;     ...
;         const char* base = (const char*)F.PG + (size_t)ud * 32768;
;         const char* bM = upin(base); const char* bB = upin(base + 8192); const char* bQ = upin(base + 16384); const char* bO = upin(base + 24576);
; #pragma unroll
;         for (int ks = 0; ks < 2; ++ks) { o.Mf[ks] = ldun<bf16x8>(bM + ks * 1024, L.o16); o.Qf[ks] = ldun<bf16x8>(bQ + ks * 1024, L.o16); }
; #pragma unroll
;         for (int pr = 0; pr < 2; ++pr) { const v4u qb = ldun<v4u>(bB + pr * 1024, L.o16p), qo = ldun<v4u>(bO + pr * 1024, L.o16p);
;             o.bv[2 * pr] = (v2u){qb.x, qb.y}; o.bv[2 * pr + 1] = (v2u){qb.z, qb.w}; o.ov[2 * pr] = (v2u){qo.x, qo.y}; o.ov[2 * pr + 1] = (v2u){qo.z, qo.w}; }
;         o.wi = (f32x4){1.f, 1.f, 1.f, 1.f};
;     ...
;     const float gl = ((const LAS float*)(St + 4 * 80 * 72))[(dir ? (s < 4 ? 3 - s : 39 - s) : s) * 2 + dir];
;     f32x4 O[NT];
; #pragma unroll
;     for (int t = 0; t < NT; ++t) {
;         const LAS bf16_t* sp2 = Sb + (16 * t + lr) * 72 + 8 * lq;
;         const bf16x8 s0 = *(const LAS bf16x8*)sp2, s1 = *(const LAS bf16x8*)(sp2 + 32);
;         const f32x4 bv = unpack4(use.bv[t]), ov = unpack4(use.ov[t]);
;         if (GDN) {
;             f32x4 o = ov, sn = S[t] * gl + bv;
;             o = __builtin_amdgcn_mfma_f32_16x16x32_bf16(use.Qf[0], s0, o, 0, 0, 0); o = __builtin_amdgcn_mfma_f32_16x16x32_bf16(use.Qf[1], s1, o, 0, 0, 0);
;             sn = __builtin_amdgcn_mfma_f32_16x16x32_bf16(use.Mf[0], s0, sn, 0, 0, 0); sn = __builtin_amdgcn_mfma_f32_16x16x32_bf16(use.Mf[1], s1, sn, 0, 0, 0);
;             S[t] = sn; O[t] = o;
.LBB0_546:
	s_min_u32 s5, s3, 33
	s_add_i32 s8, s5, 2
	s_sub_i32 s5, 37, s5
	s_and_b64 s[6:7], s[90:91], exec
	s_cselect_b32 s5, s8, s5
	s_add_i32 s5, s5, s30
	s_lshl_b32 s5, s5, 1
	s_add_i32 s6, s5, s68
	s_ashr_i32 s7, s6, 31
	s_lshl_b64 s[6:7], s[6:7], 15
	s_add_u32 s6, s35, s6
	s_addc_u32 s7, s43, s7
	s_add_u32 s10, s6, 0x2000
	s_addc_u32 s11, s7, 0
	s_add_u32 s12, s6, 0x4000
	s_addc_u32 s13, s7, 0
	s_mov_b64 s[8:9], s[6:7]
	s_add_u32 s6, s6, 0x6000
	s_addc_u32 s7, s7, 0
	global_load_dwordx4 v[102:105], v201, s[8:9] nt
	global_load_dwordx4 v[110:113], v201, s[12:13] nt
	global_load_dwordx4 v[98:101], v201, s[8:9] offset:1024 nt
	global_load_dwordx4 v[106:109], v201, s[12:13] offset:1024 nt
	global_load_dwordx4 v[70:73], v0, s[10:11] nt
	global_load_dwordx4 v[66:69], v0, s[6:7] nt
	global_load_dwordx4 v[22:25], v0, s[10:11] offset:1024 nt
	global_load_dwordx4 v[18:21], v0, s[6:7] offset:1024 nt
	s_add_i32 s6, s4, 1
	s_and_b64 s[4:5], s[90:91], exec
	s_cselect_b32 s4, s3, s6
	s_lshl_b32 s4, s4, 3
	s_add_i32 s4, s34, s4
	v_mov_b32_e32 v0, s4
	ds_read_b32 v0, v0 offset:46080
	ds_read_b128 v[204:207], v200
	ds_read_b128 v[208:211], v200 offset:64
	ds_read_b128 v[212:215], v200 offset:2304
	ds_read_b128 v[216:219], v200 offset:2368
	ds_read_b128 v[224:227], v200 offset:4608
	ds_read_b128 v[242:245], v200 offset:4672
	v_lshlrev_b32_e32 v134, 16, v94
	v_and_b32_e32 v135, 0xffff0000, v94
	v_lshlrev_b32_e32 v94, 16, v95
	v_and_b32_e32 v95, 0xffff0000, v95
	v_lshlrev_b32_e32 v130, 16, v86
	v_and_b32_e32 v131, 0xffff0000, v86
	v_lshlrev_b32_e32 v132, 16, v87
	v_and_b32_e32 v133, 0xffff0000, v87
	s_waitcnt lgkmcnt(6)
	v_fma_f32 v128, v128, v0, v94
	v_fma_f32 v129, v129, v0, v95
	v_fma_f32 v126, v126, v0, v134
	v_fma_f32 v127, v127, v0, v135
	s_waitcnt lgkmcnt(5)
	v_mfma_f32_16x16x32_bf16 v[130:133], v[46:49], v[204:207], v[130:133]
	v_lshlrev_b32_e32 v94, 16, v96
	v_and_b32_e32 v95, 0xffff0000, v96
	v_lshlrev_b32_e32 v96, 16, v97
	v_mfma_f32_16x16x32_bf16 v[204:207], v[30:33], v[204:207], v[126:129]
	v_and_b32_e32 v97, 0xffff0000, v97
	v_lshlrev_b32_e32 v86, 16, v88
	v_and_b32_e32 v87, 0xffff0000, v88
	s_waitcnt lgkmcnt(4)
	v_mfma_f32_16x16x32_bf16 v[130:133], v[34:37], v[208:211], v[130:133]
	v_lshlrev_b32_e32 v88, 16, v89
	v_and_b32_e32 v89, 0xffff0000, v89
	v_fma_f32 v96, v124, v0, v96
	v_fma_f32 v97, v125, v0, v97
	v_mfma_f32_16x16x32_bf16 v[126:129], v[26:29], v[208:211], v[204:207]
	s_nop 2
	v_fma_f32 v94, v122, v0, v94
	v_fma_f32 v95, v123, v0, v95
	s_waitcnt lgkmcnt(3)
	v_mfma_f32_16x16x32_bf16 v[86:89], v[46:49], v[212:215], v[86:89]
	s_nop 0
	v_mfma_f32_16x16x32_bf16 v[204:207], v[30:33], v[212:215], v[94:97]
	s_waitcnt lgkmcnt(2)
	v_mfma_f32_16x16x32_bf16 v[134:137], v[34:37], v[216:219], v[86:89]
	s_nop 0
	v_lshlrev_b32_e32 v94, 16, v78
	v_and_b32_e32 v95, 0xffff0000, v78
	v_lshlrev_b32_e32 v78, 16, v79
	v_mfma_f32_16x16x32_bf16 v[122:125], v[26:29], v[216:219], v[204:207]
	ds_read_b128 v[212:215], v200 offset:6912
	ds_read_b128 v[216:219], v200 offset:6976
	s_nop 2
	v_and_b32_e32 v79, 0xffff0000, v79
	v_lshlrev_b32_e32 v86, 16, v74
	v_and_b32_e32 v87, 0xffff0000, v74
	v_lshlrev_b32_e32 v88, 16, v75
	v_and_b32_e32 v89, 0xffff0000, v75
	v_fma_f32 v96, v116, v0, v78
	v_fma_f32 v97, v117, v0, v79
	v_fma_f32 v94, v114, v0, v94
	v_fma_f32 v95, v115, v0, v95
	s_waitcnt lgkmcnt(3)
	v_mfma_f32_16x16x32_bf16 v[86:89], v[46:49], v[224:227], v[86:89]
	v_lshlrev_b32_e32 v78, 16, v80
	v_and_b32_e32 v79, 0xffff0000, v80
	v_lshlrev_b32_e32 v80, 16, v81
	v_mfma_f32_16x16x32_bf16 v[204:207], v[30:33], v[224:227], v[94:97]
	v_and_b32_e32 v81, 0xffff0000, v81
	v_lshlrev_b32_e32 v74, 16, v76
	v_and_b32_e32 v75, 0xffff0000, v76
	s_waitcnt lgkmcnt(2)
	v_mfma_f32_16x16x32_bf16 v[138:141], v[34:37], v[242:245], v[86:89]
	v_lshlrev_b32_e32 v76, 16, v77
	v_and_b32_e32 v77, 0xffff0000, v77
	v_fma_f32 v80, v120, v0, v80
	v_fma_f32 v81, v121, v0, v81
	v_mfma_f32_16x16x32_bf16 v[114:117], v[26:29], v[242:245], v[204:207]
	s_nop 2
	v_fma_f32 v78, v118, v0, v78
	v_fma_f32 v79, v119, v0, v79
	s_waitcnt lgkmcnt(1)
	v_mfma_f32_16x16x32_bf16 v[46:49], v[46:49], v[212:215], v[74:77]
	v_mfma_f32_16x16x32_bf16 v[204:207], v[30:33], v[212:215], v[78:81]
	s_waitcnt lgkmcnt(0)
	v_mfma_f32_16x16x32_bf16 v[142:145], v[34:37], v[216:219], v[46:49]
	v_mfma_f32_16x16x32_bf16 v[118:121], v[26:29], v[216:219], v[204:207]

; template <bool GDN, int NT> __device__ __forceinline__ void scan_load(const Frame& F, int b, int h, int dir, const ScanLane& L, int s, ScanOps<NT>& o) {
;     ...
;         const char* base = (const char*)F.PG + (size_t)ud * 32768;
;         const char* bM = upin(base); const char* bB = upin(base + 8192); const char* bQ = upin(base + 16384); const char* bO = upin(base + 24576);
; #pragma unroll
;         for (int ks = 0; ks < 2; ++ks) { o.Mf[ks] = ldun<bf16x8>(bM + ks * 1024, L.o16); o.Qf[ks] = ldun<bf16x8>(bQ + ks * 1024, L.o16); }
; #pragma unroll
;         for (int pr = 0; pr < 2; ++pr) { const v4u qb = ldun<v4u>(bB + pr * 1024, L.o16p), qo = ldun<v4u>(bO + pr * 1024, L.o16p);
;             o.bv[2 * pr] = (v2u){qb.x, qb.y}; o.bv[2 * pr + 1] = (v2u){qb.z, qb.w}; o.ov[2 * pr] = (v2u){qo.x, qo.y}; o.ov[2 * pr + 1] = (v2u){qo.z, qo.w}; }
;         o.wi = (f32x4){1.f, 1.f, 1.f, 1.f};
;     ...
;     if (s < 36) {
; #pragma unroll
;         for (int t = 0; t < NT; ++t) *(LAS v2u*)(Sb + (16 * t + lr) * 72 + 16 * wq + 4 * lq) = pack4(S[t]); }
;     if (s == 21 || s == 3) asm volatile("s_waitcnt vmcnt(0)" ::: "memory");
;     else if (scan_needfin(s - 1)) { if (GDN) asm volatile("s_waitcnt vmcnt(14)" ::: "memory"); else asm volatile("s_waitcnt vmcnt(15)" ::: "memory"); }
;     else { if (GDN) asm volatile("s_waitcnt vmcnt(8)" ::: "memory"); else asm volatile("s_waitcnt vmcnt(9)" ::: "memory"); }
;     __syncthreads();
;     if (s > 0) {
;         const int sp = s - 1;
;         if (sp == 20 || sp == 2) { asm volatile("s_waitcnt vmcnt(0)" ::: "memory"); scan_fin_load<GDN>(F, b, h, dir, L, sp, PEND, fin); }
;         if (!nofin) scan_finish<GDN>(F, b, h, dir, L, sp, PEND, Oprev, fin);
;     }
;     if (s == 36) return false;
;     if (scan_needfin(s) && ko != 1 && ko != 3) scan_fin_load<GDN>(F, b, h, dir, L, s + 1, PEND, fin);
;     if (ko != 1 && ko != 2) scan_load<GDN, NT>(F, b, h, dir, L, s < 34 ? s + 2 : 35, ld);
;     const float gl = ((const LAS float*)(St + 4 * 80 * 72))[(dir ? (s < 4 ? 3 - s : 39 - s) : s) * 2 + dir];
;     f32x4 O[NT];
; #pragma unroll
;     for (int t = 0; t < NT; ++t) {
;         const LAS bf16_t* sp2 = Sb + (16 * t + lr) * 72 + 8 * lq;
;         const bf16x8 s0 = *(const LAS bf16x8*)sp2, s1 = *(const LAS bf16x8*)(sp2 + 32);
;         const f32x4 bv = unpack4(use.bv[t]), ov = unpack4(use.ov[t]);
;         if (GDN) {
.LBB0_571:
	s_add_i32 s12, s23, 3
	s_min_u32 s4, s12, 33
	s_add_i32 s6, s4, 2
	s_sub_i32 s7, 37, s4
	s_and_b64 s[4:5], s[90:91], exec
	s_cselect_b32 s4, s6, s7
	s_add_i32 s4, s4, s30
	s_lshl_b32 s4, s4, 1
	s_add_i32 s4, s4, s68
	s_ashr_i32 s5, s4, 31
	s_lshl_b64 s[4:5], s[4:5], 15
	s_add_u32 s4, s35, s4
	s_addc_u32 s5, s43, s5
	s_add_u32 s8, s4, 0x2000
	s_addc_u32 s9, s5, 0
	s_add_u32 s10, s4, 0x4000
	s_addc_u32 s11, s5, 0
	s_mov_b64 s[6:7], s[4:5]
	s_add_u32 s4, s4, 0x6000
	s_addc_u32 s5, s5, 0
	global_load_dwordx4 v[30:33], v34, s[6:7] nt
	global_load_dwordx4 v[46:49], v34, s[10:11] nt
	global_load_dwordx4 v[26:29], v34, s[6:7] offset:1024 nt
	s_nop 0
	global_load_dwordx4 v[34:37], v34, s[10:11] offset:1024 nt
	s_nop 0
	global_load_dwordx4 v[94:97], v0, s[8:9] nt
	global_load_dwordx4 v[86:89], v0, s[4:5] nt
	global_load_dwordx4 v[78:81], v0, s[8:9] offset:1024 nt
	global_load_dwordx4 v[74:77], v0, s[4:5] offset:1024 nt
	s_add_i32 s1, s1, s22
	s_and_b64 s[4:5], s[90:91], exec
	s_cselect_b32 s1, s12, s1
	s_lshl_b32 s4, s1, 3
	s_add_i32 s4, s34, s4
	v_mov_b32_e32 v0, s4
	ds_read_b32 v0, v0 offset:46080
	ds_read_b128 v[134:137], v200 offset:11520
	ds_read_b128 v[138:141], v200 offset:11584
	ds_read_b128 v[212:215], v200 offset:13824
	ds_read_b128 v[216:219], v200 offset:13888
	ds_read_b128 v[224:227], v200 offset:16128
	ds_read_b128 v[242:245], v200 offset:16192
	v_lshlrev_b32_e32 v142, 16, v90
	v_and_b32_e32 v143, 0xffff0000, v90
	v_lshlrev_b32_e32 v144, 16, v91
	v_and_b32_e32 v145, 0xffff0000, v91
	v_lshlrev_b32_e32 v130, 16, v82
	v_and_b32_e32 v131, 0xffff0000, v82
	v_lshlrev_b32_e32 v132, 16, v83
	v_and_b32_e32 v133, 0xffff0000, v83
	s_waitcnt lgkmcnt(6)
	v_fma_f32 v128, v128, v0, v144
	v_fma_f32 v129, v129, v0, v145
	v_fma_f32 v126, v126, v0, v142
	v_fma_f32 v127, v127, v0, v143
	s_waitcnt lgkmcnt(5)
	v_mfma_f32_16x16x32_bf16 v[130:133], v[58:61], v[134:137], v[130:133]
	v_lshlrev_b32_e32 v146, 16, v92
	v_and_b32_e32 v147, 0xffff0000, v92
	v_lshlrev_b32_e32 v148, 16, v93
	v_mfma_f32_16x16x32_bf16 v[126:129], v[42:45], v[134:137], v[126:129]
	v_and_b32_e32 v149, 0xffff0000, v93
	v_lshlrev_b32_e32 v134, 16, v84
	v_and_b32_e32 v135, 0xffff0000, v84
	s_waitcnt lgkmcnt(4)
	v_mfma_f32_16x16x32_bf16 v[130:133], v[50:53], v[138:141], v[130:133]
	v_lshlrev_b32_e32 v136, 16, v85
	v_and_b32_e32 v137, 0xffff0000, v85
	v_fma_f32 v124, v124, v0, v148
	v_fma_f32 v125, v125, v0, v149
	v_mfma_f32_16x16x32_bf16 v[126:129], v[38:41], v[138:141], v[126:129]
	v_fma_f32 v122, v122, v0, v146
	v_fma_f32 v123, v123, v0, v147
	v_lshlrev_b32_e32 v150, 16, v62
	s_waitcnt lgkmcnt(3)
	v_mfma_f32_16x16x32_bf16 v[134:137], v[58:61], v[212:215], v[134:137]
	v_and_b32_e32 v151, 0xffff0000, v62
	v_lshlrev_b32_e32 v152, 16, v63
	v_and_b32_e32 v153, 0xffff0000, v63
	v_mfma_f32_16x16x32_bf16 v[122:125], v[42:45], v[212:215], v[122:125]
	v_lshlrev_b32_e32 v138, 16, v54
	v_and_b32_e32 v139, 0xffff0000, v54
	v_lshlrev_b32_e32 v140, 16, v55
	s_waitcnt lgkmcnt(2)
	v_mfma_f32_16x16x32_bf16 v[134:137], v[50:53], v[216:219], v[134:137]
	v_and_b32_e32 v141, 0xffff0000, v55
	v_fma_f32 v116, v116, v0, v152
	v_fma_f32 v117, v117, v0, v153
	v_fma_f32 v114, v114, v0, v150
	v_fma_f32 v115, v115, v0, v151
	v_mfma_f32_16x16x32_bf16 v[122:125], v[38:41], v[216:219], v[122:125]
	ds_read_b128 v[212:215], v200 offset:18432
	ds_read_b128 v[216:219], v200 offset:18496
	v_lshlrev_b32_e32 v166, 16, v64
	v_and_b32_e32 v167, 0xffff0000, v64
	s_waitcnt lgkmcnt(3)
	v_mfma_f32_16x16x32_bf16 v[138:141], v[58:61], v[224:227], v[138:141]
	v_lshlrev_b32_e32 v168, 16, v65
	v_and_b32_e32 v169, 0xffff0000, v65
	v_fma_f32 v120, v120, v0, v168
	v_fma_f32 v121, v121, v0, v169
	v_mfma_f32_16x16x32_bf16 v[114:117], v[42:45], v[224:227], v[114:117]
	v_lshlrev_b32_e32 v142, 16, v56
	v_and_b32_e32 v143, 0xffff0000, v56
	v_lshlrev_b32_e32 v144, 16, v57
	s_waitcnt lgkmcnt(2)
	v_mfma_f32_16x16x32_bf16 v[138:141], v[50:53], v[242:245], v[138:141]
	v_and_b32_e32 v145, 0xffff0000, v57
	v_fma_f32 v118, v118, v0, v166
	v_fma_f32 v119, v119, v0, v167
	v_mov_b32_e32 v0, v192
	v_mfma_f32_16x16x32_bf16 v[114:117], v[38:41], v[242:245], v[114:117]
	s_cmp_gt_u32 s23, 31
	s_waitcnt lgkmcnt(1)
	v_mfma_f32_16x16x32_bf16 v[142:145], v[58:61], v[212:215], v[142:145]
	v_mfma_f32_16x16x32_bf16 v[118:121], v[42:45], v[212:215], v[118:121]
	v_mov_b32_e32 v146, v154
	v_mov_b32_e32 v149, v197
	v_mov_b32_e32 v148, v192
	s_waitcnt lgkmcnt(0)
	v_mfma_f32_16x16x32_bf16 v[142:145], v[50:53], v[216:219], v[142:145]
	v_mov_b32_e32 v147, v194
	v_mfma_f32_16x16x32_bf16 v[118:121], v[38:41], v[216:219], v[118:121]
	v_mov_b32_e32 v150, v196
	v_mov_b32_e32 v151, v193
	v_mov_b32_e32 v152, v195
	s_cbranch_scc1 .LBB0_582
	v_cvt_pk_bf16_f32 v150, v126, v127
	v_cvt_pk_bf16_f32 v151, v128, v129
	ds_write_b64 v199, v[150:151]
	v_cvt_pk_bf16_f32 v150, v122, v123
	v_cvt_pk_bf16_f32 v151, v124, v125
	ds_write_b64 v199, v[150:151] offset:2304
	v_cvt_pk_bf16_f32 v150, v114, v115
	v_cvt_pk_bf16_f32 v151, v116, v117
	ds_write_b64 v199, v[150:151] offset:4608
	v_cvt_pk_bf16_f32 v150, v118, v119
	v_cvt_pk_bf16_f32 v151, v120, v121
	ds_write_b64 v199, v[150:151] offset:6912
	s_sub_i32 s4, s23, 17
	s_cmp_gt_u32 s4, 14
	s_mov_b64 s[10:11], -1
	s_cbranch_scc1 .LBB0_583

; #define LAS __attribute__((address_space(3)))
; __device__ __forceinline__ f32x4 unpack4(const v2u w) { f32x4 r; r[0] = bflo(w.x); r[1] = bfhi(w.x); r[2] = bflo(w.y); r[3] = bfhi(w.y); return r; }
; template <class T> __device__ __forceinline__ T ldun(const void* ubase, unsigned boff) { return __builtin_nontemporal_load((const GAS T*)((const GAS char*)ubase + boff)); }
; __device__ __forceinline__ const char* upin(const char* p) { asm volatile("" : "+s"(p)); return p; }
; __device__ __forceinline__ char* upin(char* p) { asm volatile("" : "+s"(p)); return p; }
; template <bool GDN, int NT> __device__ __forceinline__ void scan_load(const Frame& F, int b, int h, int dir, const ScanLane& L, int s, ScanOps<NT>& o) {
;     ...
;         const char* base = (const char*)F.PG + (size_t)ud * 32768;
;         const char* bM = upin(base); const char* bB = upin(base + 8192); const char* bQ = upin(base + 16384); const char* bO = upin(base + 24576);
; #pragma unroll
;         for (int ks = 0; ks < 2; ++ks) { o.Mf[ks] = ldun<bf16x8>(bM + ks * 1024, L.o16); o.Qf[ks] = ldun<bf16x8>(bQ + ks * 1024, L.o16); }
; #pragma unroll
;         for (int pr = 0; pr < 2; ++pr) { const v4u qb = ldun<v4u>(bB + pr * 1024, L.o16p), qo = ldun<v4u>(bO + pr * 1024, L.o16p);
;             o.bv[2 * pr] = (v2u){qb.x, qb.y}; o.bv[2 * pr + 1] = (v2u){qb.z, qb.w}; o.ov[2 * pr] = (v2u){qo.x, qo.y}; o.ov[2 * pr + 1] = (v2u){qo.z, qo.w}; }
;         o.wi = (f32x4){1.f, 1.f, 1.f, 1.f};
;     ...
;     const float gl = ((const LAS float*)(St + 4 * 80 * 72))[(dir ? (s < 4 ? 3 - s : 39 - s) : s) * 2 + dir];
;     f32x4 O[NT];
; #pragma unroll
;     for (int t = 0; t < NT; ++t) {
;         const LAS bf16_t* sp2 = Sb + (16 * t + lr) * 72 + 8 * lq;
;         const bf16x8 s0 = *(const LAS bf16x8*)sp2, s1 = *(const LAS bf16x8*)(sp2 + 32);
;         const f32x4 bv = unpack4(use.bv[t]), ov = unpack4(use.ov[t]);
;         if (GDN) {
;             f32x4 o = ov, sn = S[t] * gl + bv;
;             o = __builtin_amdgcn_mfma_f32_16x16x32_bf16(use.Qf[0], s0, o, 0, 0, 0); o = __builtin_amdgcn_mfma_f32_16x16x32_bf16(use.Qf[1], s1, o, 0, 0, 0);
;             sn = __builtin_amdgcn_mfma_f32_16x16x32_bf16(use.Mf[0], s0, sn, 0, 0, 0); sn = __builtin_amdgcn_mfma_f32_16x16x32_bf16(use.Mf[1], s1, sn, 0, 0, 0);
;             S[t] = sn; O[t] = o;
.LBB0_588:
	s_min_u32 s0, s3, 33
	s_add_i32 s4, s0, 2
	s_sub_i32 s5, 37, s0
	s_and_b64 s[0:1], s[90:91], exec
	s_cselect_b32 s0, s4, s5
	s_add_i32 s0, s0, s30
	s_lshl_b32 s0, s0, 1
	s_add_i32 s0, s0, s68
	s_ashr_i32 s1, s0, 31
	s_lshl_b64 s[0:1], s[0:1], 15
	s_add_u32 s0, s35, s0
	s_addc_u32 s1, s43, s1
	s_add_u32 s6, s0, 0x2000
	s_addc_u32 s7, s1, 0
	s_add_u32 s8, s0, 0x4000
	s_addc_u32 s9, s1, 0
	s_mov_b64 s[4:5], s[0:1]
	s_add_u32 s0, s0, 0x6000
	s_addc_u32 s1, s1, 0
	global_load_dwordx4 v[42:45], v146, s[4:5] nt
	global_load_dwordx4 v[58:61], v146, s[8:9] nt
	global_load_dwordx4 v[38:41], v146, s[4:5] offset:1024 nt
	global_load_dwordx4 v[50:53], v146, s[8:9] offset:1024 nt
	global_load_dwordx4 v[90:93], v0, s[6:7] nt
	global_load_dwordx4 v[82:85], v0, s[0:1] nt
	global_load_dwordx4 v[62:65], v0, s[6:7] offset:1024 nt
	global_load_dwordx4 v[54:57], v0, s[0:1] offset:1024 nt
	s_add_i32 s4, s22, 38
	s_and_b64 s[0:1], s[90:91], exec
	s_cselect_b32 s0, s3, s4
	s_lshl_b32 s0, s0, 3
	s_add_i32 s0, s34, s0
	v_mov_b32_e32 v0, s0
	ds_read_b32 v0, v0 offset:46080
	ds_read_b128 v[134:137], v200
	ds_read_b128 v[138:141], v200 offset:64
	ds_read_b128 v[212:215], v200 offset:2304
	ds_read_b128 v[216:219], v200 offset:2368
	ds_read_b128 v[224:227], v200 offset:4608
	ds_read_b128 v[242:245], v200 offset:4672
	v_lshlrev_b32_e32 v142, 16, v70
	v_and_b32_e32 v143, 0xffff0000, v70
	v_lshlrev_b32_e32 v70, 16, v71
	v_and_b32_e32 v71, 0xffff0000, v71
	v_lshlrev_b32_e32 v130, 16, v66
	v_and_b32_e32 v131, 0xffff0000, v66
	v_lshlrev_b32_e32 v132, 16, v67
	v_and_b32_e32 v133, 0xffff0000, v67
	s_waitcnt lgkmcnt(6)
	v_fma_f32 v128, v128, v0, v70
	v_fma_f32 v129, v129, v0, v71
	v_fma_f32 v126, v126, v0, v142
	v_fma_f32 v127, v127, v0, v143
	s_waitcnt lgkmcnt(5)
	v_mfma_f32_16x16x32_bf16 v[130:133], v[110:113], v[134:137], v[130:133]
	v_lshlrev_b32_e32 v66, 16, v68
	v_and_b32_e32 v67, 0xffff0000, v68
	v_lshlrev_b32_e32 v68, 16, v69
	v_mfma_f32_16x16x32_bf16 v[126:129], v[102:105], v[134:137], v[126:129]
	v_and_b32_e32 v69, 0xffff0000, v69
	v_lshlrev_b32_e32 v70, 16, v72
	v_and_b32_e32 v71, 0xffff0000, v72
	s_waitcnt lgkmcnt(4)
	v_mfma_f32_16x16x32_bf16 v[130:133], v[106:109], v[138:141], v[130:133]
	v_lshlrev_b32_e32 v72, 16, v73
	v_and_b32_e32 v73, 0xffff0000, v73
	v_fma_f32 v72, v124, v0, v72
	v_fma_f32 v73, v125, v0, v73
	v_mfma_f32_16x16x32_bf16 v[126:129], v[98:101], v[138:141], v[126:129]
	v_fma_f32 v70, v122, v0, v70
	v_fma_f32 v71, v123, v0, v71
	s_waitcnt lgkmcnt(3)
	v_mfma_f32_16x16x32_bf16 v[66:69], v[110:113], v[212:215], v[66:69]
	s_waitcnt lgkmcnt(2)
	v_mfma_f32_16x16x32_bf16 v[134:137], v[106:109], v[216:219], v[66:69]
	v_mfma_f32_16x16x32_bf16 v[66:69], v[102:105], v[212:215], v[70:73]
	v_lshlrev_b32_e32 v138, 16, v18
	v_and_b32_e32 v139, 0xffff0000, v18
	v_lshlrev_b32_e32 v140, 16, v19
	v_mfma_f32_16x16x32_bf16 v[122:125], v[98:101], v[216:219], v[66:69]
	ds_read_b128 v[212:215], v200 offset:6912
	ds_read_b128 v[216:219], v200 offset:6976
	s_nop 3
	v_lshlrev_b32_e32 v142, 16, v22
	v_and_b32_e32 v143, 0xffff0000, v22
	v_lshlrev_b32_e32 v22, 16, v23
	v_and_b32_e32 v23, 0xffff0000, v23
	v_and_b32_e32 v141, 0xffff0000, v19
	v_fma_f32 v116, v116, v0, v22
	v_fma_f32 v117, v117, v0, v23
	v_fma_f32 v114, v114, v0, v142
	v_fma_f32 v115, v115, v0, v143
	s_waitcnt lgkmcnt(3)
	v_mfma_f32_16x16x32_bf16 v[138:141], v[110:113], v[224:227], v[138:141]
	v_lshlrev_b32_e32 v18, 16, v20
	v_and_b32_e32 v19, 0xffff0000, v20
	v_lshlrev_b32_e32 v20, 16, v21
	v_mfma_f32_16x16x32_bf16 v[66:69], v[102:105], v[224:227], v[114:117]
	v_and_b32_e32 v21, 0xffff0000, v21
	v_lshlrev_b32_e32 v22, 16, v24
	v_and_b32_e32 v23, 0xffff0000, v24
	s_waitcnt lgkmcnt(2)
	v_mfma_f32_16x16x32_bf16 v[138:141], v[106:109], v[242:245], v[138:141]
	v_lshlrev_b32_e32 v24, 16, v25
	v_and_b32_e32 v25, 0xffff0000, v25
	v_fma_f32 v24, v120, v0, v24
	v_fma_f32 v25, v121, v0, v25
	v_mfma_f32_16x16x32_bf16 v[114:117], v[98:101], v[242:245], v[66:69]
	s_nop 2
	v_fma_f32 v22, v118, v0, v22
	v_fma_f32 v23, v119, v0, v23
	s_waitcnt lgkmcnt(1)
	v_mfma_f32_16x16x32_bf16 v[18:21], v[110:113], v[212:215], v[18:21]
	s_waitcnt lgkmcnt(0)
	v_mfma_f32_16x16x32_bf16 v[142:145], v[106:109], v[216:219], v[18:21]
	v_mfma_f32_16x16x32_bf16 v[18:21], v[102:105], v[212:215], v[22:25]
	v_mfma_f32_16x16x32_bf16 v[118:121], v[98:101], v[216:219], v[18:21]
